# SwiGLU epilogue: unreachable denormal rescale around v_rsq dropped (m >= 1e-5 always)
# speedup vs baseline: 1.0058x; 1.0026x over previous
.LBB0_361:
	s_waitcnt vmcnt(0) lgkmcnt(0)
	v_mul_lo_u32 v128, v152, s42
	s_lshl_b32 s18, s47, 8
	v_lshl_add_u32 v129, v146, 1, s18
	v_add_u32_e32 v128, v128, v129
	v_fmamk_f32 v132, v167, 0x3a800000, v162
	v_cndmask_b32_e64 v134, v132, 1.0, s[14:15]
	v_pk_mul_f32 v[116:117], v[124:125], v[116:117]
	v_pk_mul_f32 v[118:119], v[126:127], v[118:119]
	v_rsq_f32_e32 v132, v132
	v_pk_mul_f32 v[112:113], v[120:121], v[112:113]
	v_pk_mul_f32 v[114:115], v[122:123], v[114:115]
	v_cndmask_b32_e64 v132, v132, 1.0, s[14:15]
	v_mul_f32_e32 v130, 0xbfb8aa3b, v132
	v_pk_mul_f32 v[124:125], v[124:125], v[130:131] op_sel_hi:[1,0]
	v_pk_mul_f32 v[126:127], v[126:127], v[130:131] op_sel_hi:[1,0]
	v_pk_mul_f32 v[120:121], v[120:121], v[130:131] op_sel_hi:[1,0]
	v_pk_mul_f32 v[122:123], v[122:123], v[130:131] op_sel_hi:[1,0]
	v_exp_f32_e32 v124, v124
	v_exp_f32_e32 v125, v125
	v_exp_f32_e32 v126, v126
	v_exp_f32_e32 v127, v127
	v_exp_f32_e32 v120, v120
	v_exp_f32_e32 v121, v121
	v_exp_f32_e32 v122, v122
	v_exp_f32_e32 v123, v123
	v_pk_fma_f32 v[124:125], v[124:125], v[134:135], v[134:135] op_sel_hi:[1,0,0]
	v_pk_fma_f32 v[126:127], v[126:127], v[134:135], v[134:135] op_sel_hi:[1,0,0]
	v_pk_fma_f32 v[120:121], v[120:121], v[134:135], v[134:135] op_sel_hi:[1,0,0]
	v_pk_fma_f32 v[122:123], v[122:123], v[134:135], v[134:135] op_sel_hi:[1,0,0]
	v_rcp_f32_e32 v124, v124
	v_rcp_f32_e32 v125, v125
	v_rcp_f32_e32 v126, v126
	v_rcp_f32_e32 v127, v127
	v_rcp_f32_e32 v120, v120
	v_rcp_f32_e32 v121, v121
	v_rcp_f32_e32 v122, v122
	v_rcp_f32_e32 v123, v123
	v_pk_mul_f32 v[116:117], v[116:117], v[124:125]
	v_pk_mul_f32 v[118:119], v[118:119], v[126:127]
	v_pk_mul_f32 v[112:113], v[112:113], v[120:121]
	v_pk_mul_f32 v[114:115], v[114:115], v[122:123]
	v_cvt_pk_bf16_f32 v124, v116, v117
	v_cvt_pk_bf16_f32 v125, v118, v119
	v_cvt_pk_bf16_f32 v126, v112, v113
	v_cvt_pk_bf16_f32 v127, v114, v115
	global_store_dwordx4 v128, v[124:127], s[28:29]
	v_fmamk_f32 v132, v168, 0x3a800000, v162
	v_cndmask_b32_e64 v134, v132, 1.0, s[14:15]
	v_pk_mul_f32 v[100:101], v[108:109], v[100:101]
	v_pk_mul_f32 v[102:103], v[110:111], v[102:103]
	v_rsq_f32_e32 v132, v132
	v_pk_mul_f32 v[96:97], v[104:105], v[96:97]
	v_pk_mul_f32 v[98:99], v[106:107], v[98:99]
	v_cndmask_b32_e64 v132, v132, 1.0, s[14:15]
	v_mul_f32_e32 v130, 0xbfb8aa3b, v132
	v_pk_mul_f32 v[108:109], v[108:109], v[130:131] op_sel_hi:[1,0]
	v_pk_mul_f32 v[110:111], v[110:111], v[130:131] op_sel_hi:[1,0]
	v_pk_mul_f32 v[104:105], v[104:105], v[130:131] op_sel_hi:[1,0]
	v_pk_mul_f32 v[106:107], v[106:107], v[130:131] op_sel_hi:[1,0]
	v_exp_f32_e32 v108, v108
	v_exp_f32_e32 v109, v109
	v_exp_f32_e32 v110, v110
	v_exp_f32_e32 v111, v111
	v_exp_f32_e32 v104, v104
	v_exp_f32_e32 v105, v105
	v_exp_f32_e32 v106, v106
	v_exp_f32_e32 v107, v107
	v_pk_fma_f32 v[108:109], v[108:109], v[134:135], v[134:135] op_sel_hi:[1,0,0]
	v_pk_fma_f32 v[110:111], v[110:111], v[134:135], v[134:135] op_sel_hi:[1,0,0]
	v_pk_fma_f32 v[104:105], v[104:105], v[134:135], v[134:135] op_sel_hi:[1,0,0]
	v_pk_fma_f32 v[106:107], v[106:107], v[134:135], v[134:135] op_sel_hi:[1,0,0]
	v_rcp_f32_e32 v108, v108
	v_rcp_f32_e32 v109, v109
	v_rcp_f32_e32 v110, v110
	v_rcp_f32_e32 v111, v111
	v_rcp_f32_e32 v104, v104
	v_rcp_f32_e32 v105, v105
	v_rcp_f32_e32 v106, v106
	v_rcp_f32_e32 v107, v107
	v_pk_mul_f32 v[100:101], v[100:101], v[108:109]
	v_pk_mul_f32 v[102:103], v[102:103], v[110:111]
	v_pk_mul_f32 v[96:97], v[96:97], v[104:105]
	v_pk_mul_f32 v[98:99], v[98:99], v[106:107]
	v_add_u32_e32 v129, 0x16000, v128
	v_cvt_pk_bf16_f32 v108, v100, v101
	v_cvt_pk_bf16_f32 v109, v102, v103
	v_cvt_pk_bf16_f32 v110, v96, v97
	v_cvt_pk_bf16_f32 v111, v98, v99
	global_store_dwordx4 v129, v[108:111], s[28:29]
	v_fmamk_f32 v132, v169, 0x3a800000, v162
	v_cndmask_b32_e64 v134, v132, 1.0, s[14:15]
	v_pk_mul_f32 v[84:85], v[92:93], v[84:85]
	v_pk_mul_f32 v[86:87], v[94:95], v[86:87]
	v_rsq_f32_e32 v132, v132
	v_pk_mul_f32 v[80:81], v[88:89], v[80:81]
	v_pk_mul_f32 v[82:83], v[90:91], v[82:83]
	v_cndmask_b32_e64 v132, v132, 1.0, s[14:15]
	v_mul_f32_e32 v130, 0xbfb8aa3b, v132
	v_pk_mul_f32 v[92:93], v[92:93], v[130:131] op_sel_hi:[1,0]
	v_pk_mul_f32 v[94:95], v[94:95], v[130:131] op_sel_hi:[1,0]
	v_pk_mul_f32 v[88:89], v[88:89], v[130:131] op_sel_hi:[1,0]
	v_pk_mul_f32 v[90:91], v[90:91], v[130:131] op_sel_hi:[1,0]
	v_exp_f32_e32 v92, v92
	v_exp_f32_e32 v93, v93
	v_exp_f32_e32 v94, v94
	v_exp_f32_e32 v95, v95
	v_exp_f32_e32 v88, v88
	v_exp_f32_e32 v89, v89
	v_exp_f32_e32 v90, v90
	v_exp_f32_e32 v91, v91
	v_pk_fma_f32 v[92:93], v[92:93], v[134:135], v[134:135] op_sel_hi:[1,0,0]
	v_pk_fma_f32 v[94:95], v[94:95], v[134:135], v[134:135] op_sel_hi:[1,0,0]
	v_pk_fma_f32 v[88:89], v[88:89], v[134:135], v[134:135] op_sel_hi:[1,0,0]
	v_pk_fma_f32 v[90:91], v[90:91], v[134:135], v[134:135] op_sel_hi:[1,0,0]
	v_rcp_f32_e32 v92, v92
	v_rcp_f32_e32 v93, v93
	v_rcp_f32_e32 v94, v94
	v_rcp_f32_e32 v95, v95
	v_rcp_f32_e32 v88, v88
	v_rcp_f32_e32 v89, v89
	v_rcp_f32_e32 v90, v90
	v_rcp_f32_e32 v91, v91
	v_pk_mul_f32 v[84:85], v[84:85], v[92:93]
	v_pk_mul_f32 v[86:87], v[86:87], v[94:95]
	v_pk_mul_f32 v[80:81], v[80:81], v[88:89]
	v_pk_mul_f32 v[82:83], v[82:83], v[90:91]
	v_add_u32_e32 v129, 0x2c000, v128
	v_cvt_pk_bf16_f32 v92, v84, v85
	v_cvt_pk_bf16_f32 v93, v86, v87
	v_cvt_pk_bf16_f32 v94, v80, v81
	v_cvt_pk_bf16_f32 v95, v82, v83
	global_store_dwordx4 v129, v[92:95], s[28:29]
	v_fmamk_f32 v132, v170, 0x3a800000, v162
	v_cndmask_b32_e64 v134, v132, 1.0, s[14:15]
	v_pk_mul_f32 v[68:69], v[76:77], v[68:69]
	v_pk_mul_f32 v[70:71], v[78:79], v[70:71]
	v_rsq_f32_e32 v132, v132
	v_pk_mul_f32 v[64:65], v[72:73], v[64:65]
	v_pk_mul_f32 v[66:67], v[74:75], v[66:67]
	v_cndmask_b32_e64 v132, v132, 1.0, s[14:15]
	v_mul_f32_e32 v130, 0xbfb8aa3b, v132
	v_pk_mul_f32 v[76:77], v[76:77], v[130:131] op_sel_hi:[1,0]
	v_pk_mul_f32 v[78:79], v[78:79], v[130:131] op_sel_hi:[1,0]
	v_pk_mul_f32 v[72:73], v[72:73], v[130:131] op_sel_hi:[1,0]
	v_pk_mul_f32 v[74:75], v[74:75], v[130:131] op_sel_hi:[1,0]
	v_exp_f32_e32 v76, v76
	v_exp_f32_e32 v77, v77
	v_exp_f32_e32 v78, v78
	v_exp_f32_e32 v79, v79
	v_exp_f32_e32 v72, v72
	v_exp_f32_e32 v73, v73
	v_exp_f32_e32 v74, v74
	v_exp_f32_e32 v75, v75
	v_pk_fma_f32 v[76:77], v[76:77], v[134:135], v[134:135] op_sel_hi:[1,0,0]
	v_pk_fma_f32 v[78:79], v[78:79], v[134:135], v[134:135] op_sel_hi:[1,0,0]
	v_pk_fma_f32 v[72:73], v[72:73], v[134:135], v[134:135] op_sel_hi:[1,0,0]
	v_pk_fma_f32 v[74:75], v[74:75], v[134:135], v[134:135] op_sel_hi:[1,0,0]
	v_rcp_f32_e32 v76, v76
	v_rcp_f32_e32 v77, v77
	v_rcp_f32_e32 v78, v78
	v_rcp_f32_e32 v79, v79
	v_rcp_f32_e32 v72, v72
	v_rcp_f32_e32 v73, v73
	v_rcp_f32_e32 v74, v74
	v_rcp_f32_e32 v75, v75
	v_pk_mul_f32 v[68:69], v[68:69], v[76:77]
	v_pk_mul_f32 v[70:71], v[70:71], v[78:79]
	v_pk_mul_f32 v[64:65], v[64:65], v[72:73]
	v_pk_mul_f32 v[66:67], v[66:67], v[74:75]
	v_add_u32_e32 v129, 0x42000, v128
	v_cvt_pk_bf16_f32 v76, v68, v69
	v_cvt_pk_bf16_f32 v77, v70, v71
	v_cvt_pk_bf16_f32 v78, v64, v65
	v_cvt_pk_bf16_f32 v79, v66, v67
	global_store_dwordx4 v129, v[76:79], s[28:29]
	v_fmamk_f32 v132, v171, 0x3a800000, v162
	v_cndmask_b32_e64 v134, v132, 1.0, s[14:15]
	v_pk_mul_f32 v[52:53], v[60:61], v[52:53]
	v_pk_mul_f32 v[54:55], v[62:63], v[54:55]
	v_rsq_f32_e32 v132, v132
	v_pk_mul_f32 v[48:49], v[56:57], v[48:49]
	v_pk_mul_f32 v[50:51], v[58:59], v[50:51]
	v_cndmask_b32_e64 v132, v132, 1.0, s[14:15]
	v_mul_f32_e32 v130, 0xbfb8aa3b, v132
	v_pk_mul_f32 v[60:61], v[60:61], v[130:131] op_sel_hi:[1,0]
	v_pk_mul_f32 v[62:63], v[62:63], v[130:131] op_sel_hi:[1,0]
	v_pk_mul_f32 v[56:57], v[56:57], v[130:131] op_sel_hi:[1,0]
	v_pk_mul_f32 v[58:59], v[58:59], v[130:131] op_sel_hi:[1,0]
	v_exp_f32_e32 v60, v60
	v_exp_f32_e32 v61, v61
	v_exp_f32_e32 v62, v62
	v_exp_f32_e32 v63, v63
	v_exp_f32_e32 v56, v56
	v_exp_f32_e32 v57, v57
	v_exp_f32_e32 v58, v58
	v_exp_f32_e32 v59, v59
	v_pk_fma_f32 v[60:61], v[60:61], v[134:135], v[134:135] op_sel_hi:[1,0,0]
	v_pk_fma_f32 v[62:63], v[62:63], v[134:135], v[134:135] op_sel_hi:[1,0,0]
	v_pk_fma_f32 v[56:57], v[56:57], v[134:135], v[134:135] op_sel_hi:[1,0,0]
	v_pk_fma_f32 v[58:59], v[58:59], v[134:135], v[134:135] op_sel_hi:[1,0,0]
	v_rcp_f32_e32 v60, v60
	v_rcp_f32_e32 v61, v61
	v_rcp_f32_e32 v62, v62
	v_rcp_f32_e32 v63, v63
	v_rcp_f32_e32 v56, v56
	v_rcp_f32_e32 v57, v57
	v_rcp_f32_e32 v58, v58
	v_rcp_f32_e32 v59, v59
	v_pk_mul_f32 v[52:53], v[52:53], v[60:61]
	v_pk_mul_f32 v[54:55], v[54:55], v[62:63]
	v_pk_mul_f32 v[48:49], v[48:49], v[56:57]
	v_pk_mul_f32 v[50:51], v[50:51], v[58:59]
	v_add_u32_e32 v129, 0xb0000, v128
	v_cvt_pk_bf16_f32 v60, v52, v53
	v_cvt_pk_bf16_f32 v61, v54, v55
	v_cvt_pk_bf16_f32 v62, v48, v49
	v_cvt_pk_bf16_f32 v63, v50, v51
	global_store_dwordx4 v129, v[60:63], s[28:29]
	v_fmamk_f32 v132, v172, 0x3a800000, v162
	v_cndmask_b32_e64 v134, v132, 1.0, s[14:15]
	v_pk_mul_f32 v[36:37], v[44:45], v[36:37]
	v_pk_mul_f32 v[38:39], v[46:47], v[38:39]
	v_rsq_f32_e32 v132, v132
	v_pk_mul_f32 v[32:33], v[40:41], v[32:33]
	v_pk_mul_f32 v[34:35], v[42:43], v[34:35]
	v_cndmask_b32_e64 v132, v132, 1.0, s[14:15]
	v_mul_f32_e32 v130, 0xbfb8aa3b, v132
	v_pk_mul_f32 v[44:45], v[44:45], v[130:131] op_sel_hi:[1,0]
	v_pk_mul_f32 v[46:47], v[46:47], v[130:131] op_sel_hi:[1,0]
	v_pk_mul_f32 v[40:41], v[40:41], v[130:131] op_sel_hi:[1,0]
	v_pk_mul_f32 v[42:43], v[42:43], v[130:131] op_sel_hi:[1,0]
	v_exp_f32_e32 v44, v44
	v_exp_f32_e32 v45, v45
	v_exp_f32_e32 v46, v46
	v_exp_f32_e32 v47, v47
	v_exp_f32_e32 v40, v40
	v_exp_f32_e32 v41, v41
	v_exp_f32_e32 v42, v42
	v_exp_f32_e32 v43, v43
	v_pk_fma_f32 v[44:45], v[44:45], v[134:135], v[134:135] op_sel_hi:[1,0,0]
	v_pk_fma_f32 v[46:47], v[46:47], v[134:135], v[134:135] op_sel_hi:[1,0,0]
	v_pk_fma_f32 v[40:41], v[40:41], v[134:135], v[134:135] op_sel_hi:[1,0,0]
	v_pk_fma_f32 v[42:43], v[42:43], v[134:135], v[134:135] op_sel_hi:[1,0,0]
	v_rcp_f32_e32 v44, v44
	v_rcp_f32_e32 v45, v45
	v_rcp_f32_e32 v46, v46
	v_rcp_f32_e32 v47, v47
	v_rcp_f32_e32 v40, v40
	v_rcp_f32_e32 v41, v41
	v_rcp_f32_e32 v42, v42
	v_rcp_f32_e32 v43, v43
	v_pk_mul_f32 v[36:37], v[36:37], v[44:45]
	v_pk_mul_f32 v[38:39], v[38:39], v[46:47]
	v_pk_mul_f32 v[32:33], v[32:33], v[40:41]
	v_pk_mul_f32 v[34:35], v[34:35], v[42:43]
	v_add_u32_e32 v129, 0xc6000, v128
	v_cvt_pk_bf16_f32 v44, v36, v37
	v_cvt_pk_bf16_f32 v45, v38, v39
	v_cvt_pk_bf16_f32 v46, v32, v33
	v_cvt_pk_bf16_f32 v47, v34, v35
	global_store_dwordx4 v129, v[44:47], s[28:29]
	v_fmamk_f32 v132, v174, 0x3a800000, v162
	v_cndmask_b32_e64 v134, v132, 1.0, s[14:15]
	v_pk_mul_f32 v[20:21], v[28:29], v[20:21]
	v_pk_mul_f32 v[22:23], v[30:31], v[22:23]
	v_rsq_f32_e32 v132, v132
	v_pk_mul_f32 v[16:17], v[24:25], v[16:17]
	v_pk_mul_f32 v[18:19], v[26:27], v[18:19]
	v_cndmask_b32_e64 v132, v132, 1.0, s[14:15]
	v_mul_f32_e32 v130, 0xbfb8aa3b, v132
	v_pk_mul_f32 v[28:29], v[28:29], v[130:131] op_sel_hi:[1,0]
	v_pk_mul_f32 v[30:31], v[30:31], v[130:131] op_sel_hi:[1,0]
	v_pk_mul_f32 v[24:25], v[24:25], v[130:131] op_sel_hi:[1,0]
	v_pk_mul_f32 v[26:27], v[26:27], v[130:131] op_sel_hi:[1,0]
	v_exp_f32_e32 v28, v28
	v_exp_f32_e32 v29, v29
	v_exp_f32_e32 v30, v30
	v_exp_f32_e32 v31, v31
	v_exp_f32_e32 v24, v24
	v_exp_f32_e32 v25, v25
	v_exp_f32_e32 v26, v26
	v_exp_f32_e32 v27, v27
	v_pk_fma_f32 v[28:29], v[28:29], v[134:135], v[134:135] op_sel_hi:[1,0,0]
	v_pk_fma_f32 v[30:31], v[30:31], v[134:135], v[134:135] op_sel_hi:[1,0,0]
	v_pk_fma_f32 v[24:25], v[24:25], v[134:135], v[134:135] op_sel_hi:[1,0,0]
	v_pk_fma_f32 v[26:27], v[26:27], v[134:135], v[134:135] op_sel_hi:[1,0,0]
	v_rcp_f32_e32 v28, v28
	v_rcp_f32_e32 v29, v29
	v_rcp_f32_e32 v30, v30
	v_rcp_f32_e32 v31, v31
	v_rcp_f32_e32 v24, v24
	v_rcp_f32_e32 v25, v25
	v_rcp_f32_e32 v26, v26
	v_rcp_f32_e32 v27, v27
	v_pk_mul_f32 v[20:21], v[20:21], v[28:29]
	v_pk_mul_f32 v[22:23], v[22:23], v[30:31]
	v_pk_mul_f32 v[16:17], v[16:17], v[24:25]
	v_pk_mul_f32 v[18:19], v[18:19], v[26:27]
	v_add_u32_e32 v129, 0xdc000, v128
	v_cvt_pk_bf16_f32 v28, v20, v21
	v_cvt_pk_bf16_f32 v29, v22, v23
	v_cvt_pk_bf16_f32 v30, v16, v17
	v_cvt_pk_bf16_f32 v31, v18, v19
	global_store_dwordx4 v129, v[28:31], s[28:29]
	v_fmamk_f32 v132, v173, 0x3a800000, v162
	v_cndmask_b32_e64 v134, v132, 1.0, s[14:15]
	v_pk_mul_f32 v[4:5], v[12:13], v[4:5]
	v_pk_mul_f32 v[6:7], v[14:15], v[6:7]
	v_rsq_f32_e32 v132, v132
	v_pk_mul_f32 v[0:1], v[8:9], v[0:1]
	v_pk_mul_f32 v[2:3], v[10:11], v[2:3]
	v_cndmask_b32_e64 v132, v132, 1.0, s[14:15]
	v_mul_f32_e32 v130, 0xbfb8aa3b, v132
	v_pk_mul_f32 v[12:13], v[12:13], v[130:131] op_sel_hi:[1,0]
	v_pk_mul_f32 v[14:15], v[14:15], v[130:131] op_sel_hi:[1,0]
	v_pk_mul_f32 v[8:9], v[8:9], v[130:131] op_sel_hi:[1,0]
	v_pk_mul_f32 v[10:11], v[10:11], v[130:131] op_sel_hi:[1,0]
	v_exp_f32_e32 v12, v12
	v_exp_f32_e32 v13, v13
	v_exp_f32_e32 v14, v14
	v_exp_f32_e32 v15, v15
	v_exp_f32_e32 v8, v8
	v_exp_f32_e32 v9, v9
	v_exp_f32_e32 v10, v10
	v_exp_f32_e32 v11, v11
	v_pk_fma_f32 v[12:13], v[12:13], v[134:135], v[134:135] op_sel_hi:[1,0,0]
	v_pk_fma_f32 v[14:15], v[14:15], v[134:135], v[134:135] op_sel_hi:[1,0,0]
	v_pk_fma_f32 v[8:9], v[8:9], v[134:135], v[134:135] op_sel_hi:[1,0,0]
	v_pk_fma_f32 v[10:11], v[10:11], v[134:135], v[134:135] op_sel_hi:[1,0,0]
	v_rcp_f32_e32 v12, v12
	v_rcp_f32_e32 v13, v13
	v_rcp_f32_e32 v14, v14
	v_rcp_f32_e32 v15, v15
	v_rcp_f32_e32 v8, v8
	v_rcp_f32_e32 v9, v9
	v_rcp_f32_e32 v10, v10
	v_rcp_f32_e32 v11, v11
	v_pk_mul_f32 v[4:5], v[4:5], v[12:13]
	v_pk_mul_f32 v[6:7], v[6:7], v[14:15]
	v_pk_mul_f32 v[0:1], v[0:1], v[8:9]
	v_pk_mul_f32 v[2:3], v[2:3], v[10:11]
	v_add_u32_e32 v129, 0xf2000, v128
	v_cvt_pk_bf16_f32 v12, v4, v5
	v_cvt_pk_bf16_f32 v13, v6, v7
	v_cvt_pk_bf16_f32 v14, v0, v1
	v_cvt_pk_bf16_f32 v15, v2, v3
	global_store_dwordx4 v129, v[12:15], s[28:29]
	s_and_b64 vcc, exec, s[38:39]
	s_cbranch_vccz .LBB0_158
